# v126 plus the two per-head constants of the beta/alpha GEMV hoisted out of the row loop (four serialized load round trips per trip removed)
# speedup vs baseline: 1.0037x; 1.0037x over previous
; __device__ __forceinline__ int ptid_(int wave) { int l_; asm volatile("v_mbcnt_lo_u32_b32 %0, -1, 0\n\tv_mbcnt_hi_u32_b32 %0, -1, %0" : "=v"(l_)); return (wave << 6) | l_; }
; __device__ void ba_item(const Params& p, int L, int rp) {
;     ...
;   const float* wba = misc + MF_WBA + (L >> 1) * 8192;
;   const float* rowss = misc + MF_RSP + (L == 0 ? 0L : 2L * MTOK * 16);
;   int tid = ptid_(p.tid); asm volatile("" : "+v"(tid));
;   const int wid = tid >> 6, lane = tid & 63;
;   f32x4 wr_[8][4];
;   _Pragma("unroll") for (int j = 0; j < 8; ++j) _Pragma("unroll") for (int e4 = 0; e4 < 4; ++e4)
;     wr_[j][e4] = *(const f32x4*)(wba + j * 1024 + lane * 16 + e4 * 4);
;   for (int bt = 0; bt < 8; ++bt) {
;     bf16x8 h0[2], h1[2]; f32x4 ps[2][4];
;     _Pragma("unroll") for (int u = 0; u < 2; ++u) {
;       const int row = rp * 128 + wid * 16 + bt * 2 + u;
;       const bfu* hr = hb + (long)row * 1024 + lane * 16;
;       h0[u] = *(const bf16x8*)hr; h1[u] = *(const bf16x8*)(hr + 8);
;       _Pragma("unroll") for (int i = 0; i < 4; ++i) ps[u][i] = *(const f32x4*)(rowss + (long)row * 16 + i * 4);
.LBB0_612:
	s_cmpk_gt_i32 s18, 0x6ff
	s_mov_b64 s[0:1], -1
	s_cbranch_scc0 .LBB0_628
	v_mbcnt_lo_u32_b32 v0, -1, 0
	v_mbcnt_hi_u32_b32 v0, -1, v0
	s_mov_b64 s[0:1], 0x1000
	s_waitcnt vmcnt(0)
	v_or_b32_e32 v130, s33, v0
	v_mov_b32_e32 v131, v1
	v_and_b32_e32 v132, 63, v130
	v_lshlrev_b32_e32 v0, 6, v132
	v_lshl_add_u64 v[114:115], s[26:27], 0, v[0:1]
	s_waitcnt lgkmcnt(0)
	v_lshl_add_u64 v[34:35], v[114:115], 0, s[0:1]
	s_mov_b64 s[0:1], 0x2000
	v_add_co_u32_e32 v30, vcc, s56, v114
	v_lshl_add_u64 v[46:47], v[114:115], 0, s[0:1]
	s_mov_b64 s[0:1], 0x3000
	v_addc_co_u32_e32 v31, vcc, 0, v115, vcc
	v_lshl_add_u64 v[66:67], v[114:115], 0, s[0:1]
	s_mov_b64 s[0:1], 0x4000
	v_add_co_u32_e32 v62, vcc, s63, v114
	s_waitcnt vmcnt(0)
	v_lshl_add_u64 v[78:79], v[114:115], 0, s[0:1]
	s_mov_b64 s[0:1], 0x5000
	v_addc_co_u32_e32 v63, vcc, 0, v115, vcc
	v_lshl_add_u64 v[98:99], v[114:115], 0, s[0:1]
	s_movk_i32 s0, 0x6000
	v_add_co_u32_e32 v94, vcc, s0, v114
	s_mov_b64 s[0:1], 0x6000
	v_lshl_add_u64 v[110:111], v[114:115], 0, s[0:1]
	s_mov_b64 s[0:1], 0x7000
	v_addc_co_u32_e32 v95, vcc, 0, v115, vcc
	v_lshl_add_u64 v[126:127], v[114:115], 0, s[0:1]
	s_movk_i32 s0, 0x7000
	global_load_dwordx4 v[2:5], v0, s[26:27]
	global_load_dwordx4 v[6:9], v0, s[26:27] offset:16
	global_load_dwordx4 v[10:13], v0, s[26:27] offset:32
	global_load_dwordx4 v[14:17], v0, s[26:27] offset:48
	global_load_dwordx4 v[18:21], v[34:35], off offset:16
	global_load_dwordx4 v[22:25], v[34:35], off offset:32
	global_load_dwordx4 v[26:29], v[30:31], off offset:-4096
	s_nop 0
	global_load_dwordx4 v[30:33], v[30:31], off
	s_nop 0
	global_load_dwordx4 v[34:37], v[34:35], off offset:48
	s_nop 0
	global_load_dwordx4 v[38:41], v[46:47], off offset:16
	global_load_dwordx4 v[42:45], v[46:47], off offset:32
	s_nop 0
	global_load_dwordx4 v[46:49], v[46:47], off offset:48
	s_nop 0
	global_load_dwordx4 v[50:53], v[66:67], off offset:16
	global_load_dwordx4 v[54:57], v[66:67], off offset:32
	global_load_dwordx4 v[58:61], v[62:63], off offset:-4096
	s_nop 0
	global_load_dwordx4 v[62:65], v[62:63], off
	s_nop 0
	global_load_dwordx4 v[66:69], v[66:67], off offset:48
	s_nop 0
	global_load_dwordx4 v[70:73], v[78:79], off offset:16
	global_load_dwordx4 v[74:77], v[78:79], off offset:32
	s_nop 0
	global_load_dwordx4 v[78:81], v[78:79], off offset:48
	s_nop 0
	global_load_dwordx4 v[82:85], v[98:99], off offset:16
	global_load_dwordx4 v[86:89], v[98:99], off offset:32
	global_load_dwordx4 v[90:93], v[94:95], off offset:-4096
	s_nop 0
	global_load_dwordx4 v[94:97], v[94:95], off
	s_nop 0
	global_load_dwordx4 v[98:101], v[98:99], off offset:48
	s_nop 0
	global_load_dwordx4 v[102:105], v[110:111], off offset:16
	global_load_dwordx4 v[106:109], v[110:111], off offset:32
	s_nop 0
	global_load_dwordx4 v[110:113], v[110:111], off offset:48
	v_add_co_u32_e32 v122, vcc, s0, v114
	v_ashrrev_i32_e32 v0, 2, v130
	s_nop 0
	v_addc_co_u32_e32 v123, vcc, 0, v115, vcc
	global_load_dwordx4 v[114:117], v[126:127], off offset:16
	global_load_dwordx4 v[118:121], v[126:127], off offset:32
	s_nop 0
	global_load_dwordx4 v[122:125], v[122:123], off
	s_nop 0
	global_load_dwordx4 v[126:129], v[126:127], off offset:48
	v_and_b32_e32 v133, -16, v0
	v_lshlrev_b32_e32 v0, 5, v132
	v_readlane_b32 s0, v252, 18
	v_lshl_add_u64 v[154:155], s[80:81], 0, v[0:1]
	v_add_u32_e32 v0, s19, v132
	v_lshlrev_b32_e32 v130, 2, v132
	v_readlane_b32 s1, v252, 19
	v_readlane_b32 s80, v253, 52
	v_xor_b32_e32 v166, 0x80, v130
	v_lshl_add_u64 v[156:157], s[0:1], 0, v[130:131]
	v_xor_b32_e32 v167, 64, v130
	v_xor_b32_e32 v168, 32, v130
	v_xor_b32_e32 v169, 16, v130
	v_xor_b32_e32 v170, 8, v130
	v_xor_b32_e32 v171, 4, v130
	v_lshlrev_b64 v[130:131], 2, v[0:1]
	v_readlane_b32 s92, v254, 0
	v_readlane_b32 s93, v254, 1
	v_readlane_b32 s94, v254, 2
	v_readlane_b32 s95, v254, 3
	v_readlane_b32 s24, v254, 62
	s_mov_b32 s22, -16
	v_cmp_gt_u32_e32 vcc, 8, v132
	v_cmp_lt_u32_e64 s[38:39], 3, v132
	v_cmp_eq_u32_e64 s[40:41], 0, v132
	v_cmp_eq_u32_e64 s[42:43], 1, v132
	v_cmp_eq_u32_e64 s[44:45], 2, v132
	v_cmp_eq_u32_e64 s[46:47], 3, v132
	v_cmp_eq_u32_e64 s[48:49], 4, v132
	v_cmp_eq_u32_e64 s[50:51], 5, v132
	v_cmp_eq_u32_e64 s[52:53], 6, v132
	v_cmp_eq_u32_e64 s[54:55], 7, v132
	v_lshl_add_u64 v[158:159], s[94:95], 0, v[130:131]
	v_lshl_add_u64 v[160:161], s[92:93], 0, v[130:131]
	v_add_u32_e32 v0, s20, v133
	v_readlane_b32 s25, v254, 63
	v_readlane_b32 s81, v253, 53
	v_readlane_b32 s82, v253, 54
	v_readlane_b32 s83, v253, 55
	v_readlane_b32 s84, v253, 56
	v_readlane_b32 s85, v253, 57
	v_readlane_b32 s86, v253, 58
	v_readlane_b32 s87, v253, 59
	v_readlane_b32 s88, v253, 60
	v_readlane_b32 s89, v253, 61
	v_readlane_b32 s90, v253, 62
	v_readlane_b32 s91, v253, 63
	s_mov_b64 s[12:13], exec
	s_mov_b64 exec, 0xf0
	global_load_dword v203, v[158:159], off
	global_load_dword v205, v[160:161], off
	s_mov_b64 exec, s[12:13]
	s_branch .LBB0_616

; __device__ __forceinline__ float bf2f(bfu h) { return __uint_as_float(((unsigned)h) << 16); }
; #define SHX(v, m) shx_((v), (m), lane)
; __device__ void ba_item(const Params& p, int L, int rp) {
;     ...
;   for (int bt = 0; bt < 8; ++bt) {
;     bf16x8 h0[2], h1[2]; f32x4 ps[2][4];
;     _Pragma("unroll") for (int u = 0; u < 2; ++u) {
;       const int row = rp * 128 + wid * 16 + bt * 2 + u;
;       const bfu* hr = hb + (long)row * 1024 + lane * 16;
;       h0[u] = *(const bf16x8*)hr; h1[u] = *(const bf16x8*)(hr + 8);
;       _Pragma("unroll") for (int i = 0; i < 4; ++i) ps[u][i] = *(const f32x4*)(rowss + (long)row * 16 + i * 4);
;     }
;     _Pragma("unroll") for (int u = 0; u < 2; ++u) {
;       const int row = rp * 128 + wid * 16 + bt * 2 + u;
;       float hf[16];
;       _Pragma("unroll") for (int e = 0; e < 8; ++e) { hf[e] = bf2f((bfu)h0[u][e]); hf[8 + e] = bf2f((bfu)h1[u][e]); }
;       float a[8];
;       _Pragma("unroll") for (int j = 0; j < 8; ++j) {
;         float s = 0.f;
;         _Pragma("unroll") for (int e4 = 0; e4 < 4; ++e4) _Pragma("unroll") for (int e = 0; e < 4; ++e) s += hf[e4 * 4 + e] * wr_[j][e4][e];
;         _Pragma("unroll") for (int o = 32; o >= 1; o >>= 1) s += SHX(s, o);
;         a[j] = s;
;       }
.LBB0_616:
	s_waitcnt vmcnt(3)
	v_add_u32_e32 v132, s22, v0
	v_add_u32_e32 v164, 0xfffc8010, v132
	s_waitcnt lgkmcnt(3)
	v_ashrrev_i32_e32 v165, 31, v164
	v_lshlrev_b64 v[130:131], 11, v[164:165]
	v_lshl_add_u64 v[130:131], v[154:155], 0, v[130:131]
	s_waitcnt lgkmcnt(1)
	global_load_dwordx4 v[172:175], v[130:131], off
	s_waitcnt lgkmcnt(0)
	global_load_dwordx4 v[176:179], v[130:131], off offset:16
	v_add_u32_e32 v162, 0xfffc8011, v132
	v_ashrrev_i32_e32 v163, 31, v162
	v_lshlrev_b64 v[130:131], 11, v[162:163]
	v_lshlrev_b64 v[132:133], 6, v[162:163]
	v_lshl_add_u64 v[130:131], v[154:155], 0, v[130:131]
	s_waitcnt vmcnt(2)
	v_lshl_add_u64 v[142:143], s[24:25], 0, v[132:133]
	global_load_dwordx4 v[146:149], v[130:131], off
	global_load_dwordx4 v[150:153], v[130:131], off offset:16
	s_nop 0
	global_load_dwordx4 v[130:133], v[142:143], off offset:48
	global_load_dwordx4 v[134:137], v[142:143], off offset:32
	global_load_dwordx4 v[138:141], v[142:143], off offset:16
	s_nop 0
	global_load_dwordx4 v[142:145], v[142:143], off
	s_waitcnt vmcnt(7)
	v_lshlrev_b32_e32 v182, 16, v172
	v_and_b32_e32 v184, 0xffff0000, v172
	s_waitcnt vmcnt(6)
	v_lshlrev_b32_e32 v187, 16, v177
	v_and_b32_e32 v189, 0xffff0000, v177
	v_fma_f32 v177, v58, v182, 0
	v_lshlrev_b32_e32 v186, 16, v173
	v_fmac_f32_e32 v177, v59, v184
	v_and_b32_e32 v188, 0xffff0000, v173
	v_fmac_f32_e32 v177, v60, v186
	v_lshlrev_b32_e32 v190, 16, v174
	v_fmac_f32_e32 v177, v61, v188
	v_and_b32_e32 v192, 0xffff0000, v174
	v_fmac_f32_e32 v177, v50, v190
	v_lshlrev_b32_e32 v194, 16, v175
	v_fmac_f32_e32 v177, v51, v192
	v_lshlrev_b32_e32 v191, 16, v178
	v_and_b32_e32 v193, 0xffff0000, v178
	v_and_b32_e32 v196, 0xffff0000, v175
	v_fma_f32 v178, v62, v182, 0
	v_fmac_f32_e32 v177, v52, v194
	v_lshlrev_b32_e32 v183, 16, v176
	v_fmac_f32_e32 v178, v63, v184
	v_fmac_f32_e32 v177, v53, v196
	v_and_b32_e32 v185, 0xffff0000, v176
	v_fmac_f32_e32 v178, v64, v186
	v_fmac_f32_e32 v177, v54, v183
	v_fmac_f32_e32 v178, v65, v188
	v_fmac_f32_e32 v177, v55, v185
	v_fmac_f32_e32 v178, v70, v190
	v_fmac_f32_e32 v177, v56, v187
	v_fmac_f32_e32 v178, v71, v192
	v_fmac_f32_e32 v177, v57, v189
	v_fmac_f32_e32 v178, v72, v194
	v_fmac_f32_e32 v177, v66, v191
	v_lshlrev_b32_e32 v195, 16, v179
	v_fmac_f32_e32 v178, v73, v196
	v_fmac_f32_e32 v177, v67, v193
	v_and_b32_e32 v197, 0xffff0000, v179
	v_fmac_f32_e32 v178, v74, v183
	v_fmac_f32_e32 v177, v68, v195
	v_fmac_f32_e32 v178, v75, v185
	v_fmac_f32_e32 v177, v69, v197
	ds_bpermute_b32 v180, v166, v177
	v_fmac_f32_e32 v178, v76, v187
	v_fmac_f32_e32 v178, v77, v189
	v_fmac_f32_e32 v178, v78, v191
	v_fmac_f32_e32 v178, v79, v193
	v_fmac_f32_e32 v178, v80, v195
	v_fmac_f32_e32 v178, v81, v197
	s_waitcnt lgkmcnt(0)
	v_add_f32_e32 v177, v177, v180
	ds_bpermute_b32 v181, v166, v178
	ds_bpermute_b32 v180, v167, v177
	v_fma_f32 v172, v2, v182, 0
	v_fma_f32 v173, v26, v182, 0
	v_fma_f32 v176, v30, v182, 0
	s_waitcnt lgkmcnt(1)
	v_add_f32_e32 v178, v178, v181
	s_waitcnt lgkmcnt(0)
	v_add_f32_e32 v177, v177, v180
	ds_bpermute_b32 v181, v167, v178
	ds_bpermute_b32 v180, v168, v177
	v_fma_f32 v200, v94, v182, 0
	v_fmac_f32_e32 v172, v3, v184
	v_fmac_f32_e32 v173, v27, v184
	s_waitcnt lgkmcnt(1)
	v_add_f32_e32 v178, v178, v181
	s_waitcnt lgkmcnt(0)
	v_add_f32_e32 v177, v177, v180
	ds_bpermute_b32 v181, v168, v178
	ds_bpermute_b32 v180, v169, v177
	v_fmac_f32_e32 v176, v31, v184
	v_fmac_f32_e32 v200, v95, v184
	v_fmac_f32_e32 v172, v4, v186
	s_waitcnt lgkmcnt(1)
	v_add_f32_e32 v178, v178, v181
	s_waitcnt lgkmcnt(0)
	v_add_f32_e32 v180, v177, v180
	ds_bpermute_b32 v181, v169, v178
	ds_bpermute_b32 v198, v170, v180
	v_fmac_f32_e32 v173, v28, v186
	v_fmac_f32_e32 v176, v32, v186
	v_fmac_f32_e32 v200, v96, v186
	s_waitcnt lgkmcnt(1)
	v_add_f32_e32 v181, v178, v181
	s_waitcnt lgkmcnt(0)
	v_add_f32_e32 v178, v180, v198
	v_fma_f32 v198, v90, v182, 0
	v_fma_f32 v182, v122, v182, 0
	v_fmac_f32_e32 v198, v91, v184
	v_fmac_f32_e32 v182, v123, v184
	v_fmac_f32_e32 v198, v92, v186
	v_fmac_f32_e32 v182, v124, v186
	v_fmac_f32_e32 v172, v5, v188
	v_fmac_f32_e32 v173, v29, v188
	v_fmac_f32_e32 v176, v33, v188
	v_fmac_f32_e32 v198, v93, v188
	v_fmac_f32_e32 v200, v97, v188
	v_fmac_f32_e32 v182, v125, v188
	v_fmac_f32_e32 v172, v6, v190
	v_fmac_f32_e32 v173, v18, v190
	v_fmac_f32_e32 v176, v38, v190
	v_fmac_f32_e32 v198, v82, v190
	v_fmac_f32_e32 v200, v102, v190
	v_fmac_f32_e32 v182, v114, v190
	v_fmac_f32_e32 v172, v7, v192
	v_fmac_f32_e32 v173, v19, v192
	v_fmac_f32_e32 v176, v39, v192
	v_fmac_f32_e32 v198, v83, v192
	v_fmac_f32_e32 v200, v103, v192
	v_fmac_f32_e32 v182, v115, v192
	v_fmac_f32_e32 v172, v8, v194
	v_fmac_f32_e32 v173, v20, v194
	v_fmac_f32_e32 v176, v40, v194
	v_fmac_f32_e32 v198, v84, v194
	v_fmac_f32_e32 v200, v104, v194
	v_fmac_f32_e32 v182, v116, v194
	v_fmac_f32_e32 v172, v9, v196
	v_fmac_f32_e32 v173, v21, v196
	v_fmac_f32_e32 v176, v41, v196
	v_fmac_f32_e32 v198, v85, v196
	v_fmac_f32_e32 v200, v105, v196
	v_fmac_f32_e32 v182, v117, v196
	v_fmac_f32_e32 v172, v10, v183
	v_fmac_f32_e32 v173, v22, v183
	v_fmac_f32_e32 v176, v42, v183
	v_fmac_f32_e32 v198, v86, v183
	v_fmac_f32_e32 v200, v106, v183
	v_fmac_f32_e32 v182, v118, v183
	v_fmac_f32_e32 v172, v11, v185
	v_fmac_f32_e32 v173, v23, v185
	v_fmac_f32_e32 v176, v43, v185
	v_fmac_f32_e32 v198, v87, v185
	v_fmac_f32_e32 v200, v107, v185
	v_fmac_f32_e32 v182, v119, v185
	v_fmac_f32_e32 v172, v12, v187
	v_fmac_f32_e32 v173, v24, v187
	v_fmac_f32_e32 v176, v44, v187
	v_fmac_f32_e32 v198, v88, v187
	v_fmac_f32_e32 v200, v108, v187
	v_fmac_f32_e32 v182, v120, v187
	v_fmac_f32_e32 v172, v13, v189
	v_fmac_f32_e32 v173, v25, v189
	v_fmac_f32_e32 v176, v45, v189
	ds_bpermute_b32 v199, v170, v181
	v_fmac_f32_e32 v198, v89, v189
	v_fmac_f32_e32 v200, v109, v189
	v_fmac_f32_e32 v182, v121, v189
	v_fmac_f32_e32 v172, v14, v191
	v_fmac_f32_e32 v173, v34, v191
	v_fmac_f32_e32 v176, v46, v191
	v_fmac_f32_e32 v198, v98, v191
	v_fmac_f32_e32 v200, v110, v191
	v_fmac_f32_e32 v182, v126, v191
	v_fmac_f32_e32 v172, v15, v193
	v_fmac_f32_e32 v173, v35, v193
	v_fmac_f32_e32 v176, v47, v193
	v_fmac_f32_e32 v198, v99, v193
	v_fmac_f32_e32 v200, v111, v193
	v_fmac_f32_e32 v182, v127, v193
	v_fmac_f32_e32 v172, v16, v195
	v_fmac_f32_e32 v173, v36, v195
	v_fmac_f32_e32 v176, v48, v195
	v_fmac_f32_e32 v198, v100, v195
	v_fmac_f32_e32 v200, v112, v195
	v_fmac_f32_e32 v182, v128, v195
	v_fmac_f32_e32 v172, v17, v197
	v_fmac_f32_e32 v173, v37, v197
	v_fmac_f32_e32 v176, v49, v197
	v_fmac_f32_e32 v198, v101, v197
	v_fmac_f32_e32 v200, v113, v197
	v_fmac_f32_e32 v182, v129, v197
	ds_bpermute_b32 v174, v166, v172
	ds_bpermute_b32 v175, v166, v173
	ds_bpermute_b32 v179, v166, v176
	s_waitcnt lgkmcnt(3)
; __device__ __forceinline__ float fexp(float x) { return __builtin_amdgcn_exp2f(x * 1.4426950408889634f); }
; __device__ __forceinline__ float flog(float x) { return __builtin_amdgcn_logf(x) * 0.6931471805599453f; }
; __device__ __forceinline__ float frsq(float x) { return __builtin_amdgcn_rsqf(x); }
; __device__ __forceinline__ float sigmoidf_(float x) { return frcp(1.0f + fexp(-x)); }
; #define SHX(v, m) shx_((v), (m), lane)
; __device__ void ba_item(const Params& p, int L, int rp) {
;     ...
;         _Pragma("unroll") for (int o = 32; o >= 1; o >>= 1) s += SHX(s, o);
;         a[j] = s;
;       }
;       if (lane < 8) {
;         float s16 = 0.f;
;         _Pragma("unroll") for (int i = 0; i < 4; ++i) s16 += (ps[u][i][0] + ps[u][i][1]) + (ps[u][i][2] + ps[u][i][3]);
;         float rs = frsq(s16 * (1.0f / 1024.0f) + 1e-6f);
;         float v = 0.f;
;         _Pragma("unroll") for (int j = 0; j < 8; ++j) if (lane == j) v = a[j];
;         v *= rs;
;         float r;
;         if (lane < 4) r = sigmoidf_(v);
;         else {
;           int hh = lane - 4;
;           float z = v + p.dn_dt_bias[(L >> 1) * 4 + hh];
;           float sp = (z > 20.f) ? z : flog(1.0f + fexp(z));
;           r = -fexp(p.dn_a_log[(L >> 1) * 4 + hh]) * sp;
;         }
;         miscw[MF_BG + (long)row * 8 + lane] = r;
	v_add_f32_e32 v180, v181, v199
	ds_bpermute_b32 v199, v166, v198
	ds_bpermute_b32 v202, v166, v200
	ds_bpermute_b32 v183, v166, v182
	s_waitcnt lgkmcnt(5)
	v_add_f32_e32 v172, v172, v174
	s_waitcnt lgkmcnt(4)
	v_add_f32_e32 v173, v173, v175
	s_waitcnt lgkmcnt(3)
	v_add_f32_e32 v176, v176, v179
	s_waitcnt lgkmcnt(2)
	v_add_f32_e32 v184, v198, v199
	s_waitcnt lgkmcnt(1)
	v_add_f32_e32 v186, v200, v202
	s_waitcnt lgkmcnt(0)
	v_add_f32_e32 v182, v182, v183
	ds_bpermute_b32 v174, v167, v172
	ds_bpermute_b32 v175, v167, v173
	ds_bpermute_b32 v179, v167, v176
	ds_bpermute_b32 v185, v167, v184
	ds_bpermute_b32 v187, v167, v186
	ds_bpermute_b32 v183, v167, v182
	s_waitcnt lgkmcnt(5)
	v_add_f32_e32 v172, v172, v174
	s_waitcnt lgkmcnt(4)
	v_add_f32_e32 v173, v173, v175
	s_waitcnt lgkmcnt(3)
	v_add_f32_e32 v176, v176, v179
	s_waitcnt lgkmcnt(2)
	v_add_f32_e32 v184, v184, v185
	s_waitcnt lgkmcnt(1)
	v_add_f32_e32 v186, v186, v187
	s_waitcnt lgkmcnt(0)
	v_add_f32_e32 v182, v182, v183
	ds_bpermute_b32 v174, v168, v172
	ds_bpermute_b32 v175, v168, v173
	ds_bpermute_b32 v179, v168, v176
	ds_bpermute_b32 v185, v168, v184
	ds_bpermute_b32 v187, v168, v186
	ds_bpermute_b32 v183, v168, v182
	s_waitcnt lgkmcnt(5)
	v_add_f32_e32 v172, v172, v174
	s_waitcnt lgkmcnt(4)
	v_add_f32_e32 v173, v173, v175
	s_waitcnt lgkmcnt(3)
	v_add_f32_e32 v176, v176, v179
	s_waitcnt lgkmcnt(2)
	v_add_f32_e32 v184, v184, v185
	s_waitcnt lgkmcnt(1)
	v_add_f32_e32 v186, v186, v187
	s_waitcnt lgkmcnt(0)
	v_add_f32_e32 v182, v182, v183
	ds_bpermute_b32 v174, v169, v172
	ds_bpermute_b32 v175, v169, v173
	ds_bpermute_b32 v179, v169, v176
	ds_bpermute_b32 v185, v169, v184
	ds_bpermute_b32 v187, v169, v186
	ds_bpermute_b32 v183, v169, v182
	s_waitcnt lgkmcnt(5)
	v_add_f32_e32 v172, v172, v174
	s_waitcnt lgkmcnt(4)
	v_add_f32_e32 v173, v173, v175
	s_waitcnt lgkmcnt(3)
	v_add_f32_e32 v176, v176, v179
	s_waitcnt lgkmcnt(2)
	v_add_f32_e32 v184, v184, v185
	s_waitcnt lgkmcnt(1)
	v_add_f32_e32 v186, v186, v187
	s_waitcnt lgkmcnt(0)
	v_add_f32_e32 v188, v182, v183
	ds_bpermute_b32 v174, v170, v172
	ds_bpermute_b32 v175, v170, v173
	ds_bpermute_b32 v179, v170, v176
	ds_bpermute_b32 v185, v170, v184
	ds_bpermute_b32 v187, v170, v186
	ds_bpermute_b32 v189, v170, v188
	s_waitcnt lgkmcnt(5)
	v_add_f32_e32 v172, v172, v174
	s_waitcnt lgkmcnt(4)
	v_add_f32_e32 v174, v173, v175
	s_waitcnt lgkmcnt(3)
	v_add_f32_e32 v176, v176, v179
	s_waitcnt lgkmcnt(2)
	v_add_f32_e32 v182, v184, v185
	s_waitcnt lgkmcnt(1)
	v_add_f32_e32 v184, v186, v187
	s_waitcnt lgkmcnt(0)
	v_add_f32_e32 v186, v188, v189
	ds_bpermute_b32 v173, v171, v172
	ds_bpermute_b32 v175, v171, v174
	ds_bpermute_b32 v177, v171, v176
	ds_bpermute_b32 v179, v171, v178
	ds_bpermute_b32 v181, v171, v180
	ds_bpermute_b32 v183, v171, v182
	ds_bpermute_b32 v185, v171, v184
	ds_bpermute_b32 v187, v171, v186
	s_and_saveexec_b64 s[12:13], vcc
	s_cbranch_execz .LBB0_622
	s_waitcnt lgkmcnt(7)
	v_add_f32_e32 v195, v172, v173
	v_lshlrev_b64 v[172:173], 6, v[164:165]
	s_waitcnt lgkmcnt(1)
	v_add_f32_e32 v189, v184, v185
	v_lshl_add_u64 v[184:185], s[24:25], 0, v[172:173]
	s_waitcnt lgkmcnt(0)
	v_add_f32_e32 v188, v186, v187
	v_add_f32_e32 v190, v182, v183
	v_add_f32_e32 v191, v180, v181
	v_add_f32_e32 v192, v178, v179
	v_add_f32_e32 v193, v176, v177
	v_add_f32_e32 v194, v174, v175
	global_load_dwordx4 v[172:175], v[184:185], off offset:48
	global_load_dwordx4 v[176:179], v[184:185], off offset:32
	global_load_dwordx4 v[180:183], v[184:185], off offset:16
	s_nop 0
	global_load_dwordx4 v[184:187], v[184:185], off
	s_waitcnt vmcnt(3)
	v_add_f32_e32 v172, v172, v173
	s_waitcnt vmcnt(2)
	v_add_f32_e32 v176, v176, v177
	s_waitcnt vmcnt(1)
	v_add_f32_e32 v180, v180, v181
	s_waitcnt vmcnt(0)
	v_add_f32_e32 v184, v184, v185
	v_add_f32_e32 v185, v186, v187
	v_add_f32_e32 v184, v184, v185
	v_add_f32_e32 v181, v182, v183
	v_add_f32_e32 v184, 0, v184
	v_add_f32_e32 v180, v180, v181
	v_add_f32_e32 v177, v178, v179
	v_add_f32_e32 v173, v174, v175
	v_add_f32_e32 v180, v180, v184
	v_add_f32_e32 v176, v176, v177
	v_add_f32_e32 v172, v172, v173
	v_cndmask_b32_e64 v173, 0, v195, s[40:41]
	v_add_f32_e32 v176, v176, v180
	v_cndmask_b32_e64 v173, v173, v194, s[42:43]
	v_add_f32_e32 v172, v172, v176
	v_cndmask_b32_e64 v173, v173, v193, s[44:45]
	v_fmamk_f32 v172, v172, 0x3a800000, v201
	v_cndmask_b32_e64 v173, v173, v192, s[46:47]
	v_cndmask_b32_e64 v173, v173, v191, s[48:49]
	v_rsq_f32_e32 v172, v172
	v_cndmask_b32_e64 v173, v173, v190, s[50:51]
	v_cndmask_b32_e64 v173, v173, v189, s[52:53]
	v_cndmask_b32_e64 v173, v173, v188, s[54:55]
	v_mul_f32_e32 v173, v173, v172
	s_and_saveexec_b64 s[0:1], s[38:39]
	s_xor_b64 s[14:15], exec, s[0:1]
	s_cbranch_execz .LBB0_619
	v_mov_b32_e32 v172, v203
	s_waitcnt vmcnt(0)
	v_add_f32_e32 v172, v173, v172
	v_mul_f32_e32 v173, 0x3fb8aa3b, v172
	v_exp_f32_e32 v173, v173
	v_cmp_lt_f32_e64 s[0:1], s57, v172
	v_add_f32_e32 v173, 1.0, v173
	v_log_f32_e32 v173, v173
	s_nop 0
	v_mul_f32_e32 v173, 0x3f317218, v173
	v_cndmask_b32_e64 v172, v173, v172, s[0:1]
	v_mov_b32_e32 v173, v205
	s_waitcnt vmcnt(0)
	v_mul_f32_e32 v173, 0x3fb8aa3b, v173
	v_exp_f32_e32 v173, v173
	s_nop 0
	v_mul_f32_e64 v172, v172, -v173

; __device__ __forceinline__ float bf2f(bfu h) { return __uint_as_float(((unsigned)h) << 16); }
; #define SHX(v, m) shx_((v), (m), lane)
; __device__ void ba_item(const Params& p, int L, int rp) {
;     ...
;     _Pragma("unroll") for (int u = 0; u < 2; ++u) {
;       const int row = rp * 128 + wid * 16 + bt * 2 + u;
;       float hf[16];
;       _Pragma("unroll") for (int e = 0; e < 8; ++e) { hf[e] = bf2f((bfu)h0[u][e]); hf[8 + e] = bf2f((bfu)h1[u][e]); }
;       float a[8];
;       _Pragma("unroll") for (int j = 0; j < 8; ++j) {
;         float s = 0.f;
;         _Pragma("unroll") for (int e4 = 0; e4 < 4; ++e4) _Pragma("unroll") for (int e = 0; e < 4; ++e) s += hf[e4 * 4 + e] * wr_[j][e4][e];
;         _Pragma("unroll") for (int o = 32; o >= 1; o >>= 1) s += SHX(s, o);
;         a[j] = s;
;       }
.LBB0_622:
	s_or_b64 exec, exec, s[12:13]
	s_waitcnt vmcnt(5)
	v_lshlrev_b32_e32 v172, 16, v146
	s_waitcnt vmcnt(4) lgkmcnt(7)
	v_lshlrev_b32_e32 v173, 16, v150
	v_and_b32_e32 v174, 0xffff0000, v146
	s_waitcnt lgkmcnt(6)
	v_and_b32_e32 v175, 0xffff0000, v150
	v_lshlrev_b32_e32 v180, 16, v148
	s_waitcnt lgkmcnt(3)
	v_lshlrev_b32_e32 v181, 16, v152
	v_and_b32_e32 v182, 0xffff0000, v148
	s_waitcnt lgkmcnt(2)
	v_and_b32_e32 v183, 0xffff0000, v152
	v_fma_f32 v146, v2, v172, 0
	v_fma_f32 v148, v26, v172, 0
	v_fma_f32 v150, v30, v172, 0
	v_fma_f32 v152, v58, v172, 0
	v_fma_f32 v164, v62, v172, 0
	v_fma_f32 v188, v90, v172, 0
	v_fma_f32 v190, v94, v172, 0
	v_fma_f32 v172, v122, v172, 0
	v_lshlrev_b32_e32 v176, 16, v147
	v_fmac_f32_e32 v146, v3, v174
	v_fmac_f32_e32 v148, v27, v174
	v_fmac_f32_e32 v150, v31, v174
	v_fmac_f32_e32 v152, v59, v174
	v_fmac_f32_e32 v164, v63, v174
	v_fmac_f32_e32 v188, v91, v174
	v_fmac_f32_e32 v190, v95, v174
	v_fmac_f32_e32 v172, v123, v174
	v_and_b32_e32 v178, 0xffff0000, v147
	v_fmac_f32_e32 v146, v4, v176
	v_fmac_f32_e32 v148, v28, v176
	v_fmac_f32_e32 v150, v32, v176
	v_fmac_f32_e32 v152, v60, v176
	v_fmac_f32_e32 v164, v64, v176
	v_fmac_f32_e32 v188, v92, v176
	v_fmac_f32_e32 v190, v96, v176
	v_fmac_f32_e32 v172, v124, v176
	v_fmac_f32_e32 v146, v5, v178
	v_fmac_f32_e32 v148, v29, v178
	v_fmac_f32_e32 v150, v33, v178
	v_fmac_f32_e32 v152, v61, v178
	v_fmac_f32_e32 v164, v65, v178
	v_fmac_f32_e32 v188, v93, v178
	v_fmac_f32_e32 v190, v97, v178
	v_fmac_f32_e32 v172, v125, v178
	v_fmac_f32_e32 v146, v6, v180
	v_fmac_f32_e32 v148, v18, v180
	v_fmac_f32_e32 v150, v38, v180
	v_fmac_f32_e32 v152, v50, v180
	v_fmac_f32_e32 v164, v70, v180
	v_fmac_f32_e32 v188, v82, v180
	v_fmac_f32_e32 v190, v102, v180
	v_fmac_f32_e32 v172, v114, v180
	v_lshlrev_b32_e32 v184, 16, v149
	v_fmac_f32_e32 v146, v7, v182
	v_fmac_f32_e32 v148, v19, v182
	v_fmac_f32_e32 v150, v39, v182
	v_fmac_f32_e32 v152, v51, v182
	v_fmac_f32_e32 v164, v71, v182
	v_fmac_f32_e32 v188, v83, v182
	v_fmac_f32_e32 v190, v103, v182
	v_fmac_f32_e32 v172, v115, v182
	v_and_b32_e32 v186, 0xffff0000, v149
	v_fmac_f32_e32 v146, v8, v184
	v_fmac_f32_e32 v148, v20, v184
	v_fmac_f32_e32 v150, v40, v184
	v_fmac_f32_e32 v152, v52, v184
	v_fmac_f32_e32 v164, v72, v184
	v_fmac_f32_e32 v188, v84, v184
	v_fmac_f32_e32 v190, v104, v184
	v_fmac_f32_e32 v172, v116, v184
	v_fmac_f32_e32 v146, v9, v186
	v_fmac_f32_e32 v148, v21, v186
	v_fmac_f32_e32 v150, v41, v186
	v_fmac_f32_e32 v152, v53, v186
	v_fmac_f32_e32 v164, v73, v186
	v_fmac_f32_e32 v188, v85, v186
	v_fmac_f32_e32 v190, v105, v186
	v_fmac_f32_e32 v172, v117, v186
	v_fmac_f32_e32 v146, v10, v173
	v_fmac_f32_e32 v148, v22, v173
	v_fmac_f32_e32 v150, v42, v173
	v_fmac_f32_e32 v152, v54, v173
	v_fmac_f32_e32 v164, v74, v173
	v_fmac_f32_e32 v188, v86, v173
	v_fmac_f32_e32 v190, v106, v173
	v_fmac_f32_e32 v172, v118, v173
	v_lshlrev_b32_e32 v177, 16, v151
	v_fmac_f32_e32 v146, v11, v175
	v_fmac_f32_e32 v148, v23, v175
	v_fmac_f32_e32 v150, v43, v175
	v_fmac_f32_e32 v152, v55, v175
	v_fmac_f32_e32 v164, v75, v175
	v_fmac_f32_e32 v188, v87, v175
	v_fmac_f32_e32 v190, v107, v175
	v_fmac_f32_e32 v172, v119, v175
	v_and_b32_e32 v179, 0xffff0000, v151
	v_fmac_f32_e32 v146, v12, v177
	v_fmac_f32_e32 v148, v24, v177
	v_fmac_f32_e32 v150, v44, v177
	v_fmac_f32_e32 v152, v56, v177
	v_fmac_f32_e32 v164, v76, v177
	v_fmac_f32_e32 v188, v88, v177
	v_fmac_f32_e32 v190, v108, v177
	v_fmac_f32_e32 v172, v120, v177
	v_fmac_f32_e32 v146, v13, v179
	v_fmac_f32_e32 v148, v25, v179
	v_fmac_f32_e32 v150, v45, v179
	v_fmac_f32_e32 v152, v57, v179
	v_fmac_f32_e32 v164, v77, v179
	v_fmac_f32_e32 v188, v89, v179
	v_fmac_f32_e32 v190, v109, v179
	v_fmac_f32_e32 v172, v121, v179
	v_fmac_f32_e32 v146, v14, v181
	v_fmac_f32_e32 v148, v34, v181
	v_fmac_f32_e32 v150, v46, v181
	v_fmac_f32_e32 v152, v66, v181
	v_fmac_f32_e32 v164, v78, v181
	v_fmac_f32_e32 v188, v98, v181
	v_fmac_f32_e32 v190, v110, v181
	v_fmac_f32_e32 v172, v126, v181
	s_waitcnt lgkmcnt(1)
	v_lshlrev_b32_e32 v185, 16, v153
	v_fmac_f32_e32 v146, v15, v183
	v_fmac_f32_e32 v148, v35, v183
	v_fmac_f32_e32 v150, v47, v183
	v_fmac_f32_e32 v152, v67, v183
	v_fmac_f32_e32 v164, v79, v183
	v_fmac_f32_e32 v188, v99, v183
	v_fmac_f32_e32 v190, v111, v183
	v_fmac_f32_e32 v172, v127, v183
	s_waitcnt lgkmcnt(0)
	v_and_b32_e32 v187, 0xffff0000, v153
	v_fmac_f32_e32 v146, v16, v185
	v_fmac_f32_e32 v148, v36, v185
	v_fmac_f32_e32 v150, v48, v185
	v_fmac_f32_e32 v152, v68, v185
	v_fmac_f32_e32 v164, v80, v185
	v_fmac_f32_e32 v188, v100, v185
	v_fmac_f32_e32 v190, v112, v185
	v_fmac_f32_e32 v172, v128, v185
	v_fmac_f32_e32 v146, v17, v187
	v_fmac_f32_e32 v148, v37, v187
	v_fmac_f32_e32 v150, v49, v187
	v_fmac_f32_e32 v152, v69, v187
	v_fmac_f32_e32 v164, v81, v187
	v_fmac_f32_e32 v188, v101, v187
	v_fmac_f32_e32 v190, v113, v187
	v_fmac_f32_e32 v172, v129, v187
	ds_bpermute_b32 v147, v166, v146
	ds_bpermute_b32 v149, v166, v148
	ds_bpermute_b32 v151, v166, v150
	ds_bpermute_b32 v153, v166, v152
	ds_bpermute_b32 v165, v166, v164
	ds_bpermute_b32 v189, v166, v188
	ds_bpermute_b32 v191, v166, v190
	ds_bpermute_b32 v173, v166, v172
	s_waitcnt lgkmcnt(7)
	v_add_f32_e32 v146, v146, v147
	s_waitcnt lgkmcnt(6)
	v_add_f32_e32 v148, v148, v149
	s_waitcnt lgkmcnt(5)
	v_add_f32_e32 v150, v150, v151
	s_waitcnt lgkmcnt(4)
	v_add_f32_e32 v152, v152, v153
	s_waitcnt lgkmcnt(3)
; __device__ __forceinline__ float fexp(float x) { return __builtin_amdgcn_exp2f(x * 1.4426950408889634f); }
; __device__ __forceinline__ float flog(float x) { return __builtin_amdgcn_logf(x) * 0.6931471805599453f; }
; __device__ __forceinline__ float frsq(float x) { return __builtin_amdgcn_rsqf(x); }
; __device__ __forceinline__ float sigmoidf_(float x) { return frcp(1.0f + fexp(-x)); }
; #define SHX(v, m) shx_((v), (m), lane)
; __device__ void ba_item(const Params& p, int L, int rp) {
;     ...
;         _Pragma("unroll") for (int o = 32; o >= 1; o >>= 1) s += SHX(s, o);
;         a[j] = s;
;       }
;       if (lane < 8) {
;         float s16 = 0.f;
;         _Pragma("unroll") for (int i = 0; i < 4; ++i) s16 += (ps[u][i][0] + ps[u][i][1]) + (ps[u][i][2] + ps[u][i][3]);
;         float rs = frsq(s16 * (1.0f / 1024.0f) + 1e-6f);
;         float v = 0.f;
;         _Pragma("unroll") for (int j = 0; j < 8; ++j) if (lane == j) v = a[j];
;         v *= rs;
;         float r;
;         if (lane < 4) r = sigmoidf_(v);
;         else {
;           int hh = lane - 4;
;           float z = v + p.dn_dt_bias[(L >> 1) * 4 + hh];
;           float sp = (z > 20.f) ? z : flog(1.0f + fexp(z));
;           r = -fexp(p.dn_a_log[(L >> 1) * 4 + hh]) * sp;
;         }
;         miscw[MF_BG + (long)row * 8 + lane] = r;
	v_add_f32_e32 v164, v164, v165
	s_waitcnt lgkmcnt(2)
	v_add_f32_e32 v174, v188, v189
	s_waitcnt lgkmcnt(1)
	v_add_f32_e32 v176, v190, v191
	s_waitcnt lgkmcnt(0)
	v_add_f32_e32 v172, v172, v173
	ds_bpermute_b32 v147, v167, v146
	ds_bpermute_b32 v149, v167, v148
	ds_bpermute_b32 v151, v167, v150
	ds_bpermute_b32 v153, v167, v152
	ds_bpermute_b32 v165, v167, v164
	ds_bpermute_b32 v175, v167, v174
	ds_bpermute_b32 v177, v167, v176
	ds_bpermute_b32 v173, v167, v172
	s_waitcnt lgkmcnt(7)
	v_add_f32_e32 v146, v146, v147
	s_waitcnt lgkmcnt(6)
	v_add_f32_e32 v148, v148, v149
	s_waitcnt lgkmcnt(5)
	v_add_f32_e32 v150, v150, v151
	s_waitcnt lgkmcnt(4)
	v_add_f32_e32 v152, v152, v153
	s_waitcnt lgkmcnt(3)
	v_add_f32_e32 v164, v164, v165
	s_waitcnt lgkmcnt(2)
	v_add_f32_e32 v174, v174, v175
	s_waitcnt lgkmcnt(1)
	v_add_f32_e32 v176, v176, v177
	s_waitcnt lgkmcnt(0)
	v_add_f32_e32 v172, v172, v173
	ds_bpermute_b32 v147, v168, v146
	ds_bpermute_b32 v149, v168, v148
	ds_bpermute_b32 v151, v168, v150
	ds_bpermute_b32 v153, v168, v152
	ds_bpermute_b32 v165, v168, v164
	ds_bpermute_b32 v175, v168, v174
	ds_bpermute_b32 v177, v168, v176
	ds_bpermute_b32 v173, v168, v172
	s_waitcnt lgkmcnt(7)
	v_add_f32_e32 v146, v146, v147
	s_waitcnt lgkmcnt(6)
	v_add_f32_e32 v148, v148, v149
	s_waitcnt lgkmcnt(5)
	v_add_f32_e32 v150, v150, v151
	s_waitcnt lgkmcnt(4)
	v_add_f32_e32 v152, v152, v153
	s_waitcnt lgkmcnt(3)
	v_add_f32_e32 v164, v164, v165
	s_waitcnt lgkmcnt(2)
	v_add_f32_e32 v174, v174, v175
	s_waitcnt lgkmcnt(1)
	v_add_f32_e32 v176, v176, v177
	s_waitcnt lgkmcnt(0)
	v_add_f32_e32 v172, v172, v173
	ds_bpermute_b32 v147, v169, v146
	ds_bpermute_b32 v149, v169, v148
	ds_bpermute_b32 v151, v169, v150
	ds_bpermute_b32 v153, v169, v152
	ds_bpermute_b32 v165, v169, v164
	ds_bpermute_b32 v175, v169, v174
	ds_bpermute_b32 v177, v169, v176
	ds_bpermute_b32 v173, v169, v172
	s_waitcnt lgkmcnt(7)
	v_add_f32_e32 v146, v146, v147
	s_waitcnt lgkmcnt(6)
	v_add_f32_e32 v148, v148, v149
	s_waitcnt lgkmcnt(5)
	v_add_f32_e32 v150, v150, v151
	s_waitcnt lgkmcnt(4)
	v_add_f32_e32 v152, v152, v153
	s_waitcnt lgkmcnt(3)
	v_add_f32_e32 v164, v164, v165
	s_waitcnt lgkmcnt(2)
	v_add_f32_e32 v174, v174, v175
	s_waitcnt lgkmcnt(1)
	v_add_f32_e32 v176, v176, v177
	s_waitcnt lgkmcnt(0)
	v_add_f32_e32 v178, v172, v173
	ds_bpermute_b32 v147, v170, v146
	ds_bpermute_b32 v149, v170, v148
	ds_bpermute_b32 v151, v170, v150
	ds_bpermute_b32 v153, v170, v152
	ds_bpermute_b32 v165, v170, v164
	ds_bpermute_b32 v175, v170, v174
	ds_bpermute_b32 v177, v170, v176
	ds_bpermute_b32 v179, v170, v178
	s_waitcnt lgkmcnt(7)
	v_add_f32_e32 v146, v146, v147
	s_waitcnt lgkmcnt(6)
	v_add_f32_e32 v148, v148, v149
	s_waitcnt lgkmcnt(5)
	v_add_f32_e32 v150, v150, v151
	s_waitcnt lgkmcnt(4)
	v_add_f32_e32 v152, v152, v153
	s_waitcnt lgkmcnt(3)
	v_add_f32_e32 v164, v164, v165
	s_waitcnt lgkmcnt(2)
	v_add_f32_e32 v172, v174, v175
	s_waitcnt lgkmcnt(1)
	v_add_f32_e32 v174, v176, v177
	s_waitcnt lgkmcnt(0)
	v_add_f32_e32 v176, v178, v179
	ds_bpermute_b32 v147, v171, v146
	ds_bpermute_b32 v149, v171, v148
	ds_bpermute_b32 v151, v171, v150
	ds_bpermute_b32 v153, v171, v152
	ds_bpermute_b32 v165, v171, v164
	ds_bpermute_b32 v173, v171, v172
	ds_bpermute_b32 v175, v171, v174
	ds_bpermute_b32 v177, v171, v176
	s_and_saveexec_b64 s[12:13], vcc
	s_cbranch_execz .LBB0_615
	s_waitcnt vmcnt(0)
	v_add_f32_e32 v142, v142, v143
	v_add_f32_e32 v143, v144, v145
	v_add_f32_e32 v142, v142, v143
	v_add_f32_e32 v138, v138, v139
	v_add_f32_e32 v139, v140, v141
	s_waitcnt lgkmcnt(7)
	v_add_f32_e32 v146, v146, v147
	v_add_f32_e32 v142, 0, v142
	v_add_f32_e32 v138, v138, v139
	v_add_f32_e32 v134, v134, v135
	v_add_f32_e32 v135, v136, v137
	v_add_f32_e32 v130, v130, v131
	v_add_f32_e32 v131, v132, v133
	s_waitcnt lgkmcnt(6)
	v_add_f32_e32 v148, v148, v149
	v_add_f32_e32 v138, v142, v138
	v_add_f32_e32 v134, v134, v135
	v_add_f32_e32 v130, v130, v131
	v_cndmask_b32_e64 v131, 0, v146, s[40:41]
	s_waitcnt lgkmcnt(5)
	v_add_f32_e32 v150, v150, v151
	v_add_f32_e32 v134, v138, v134
	v_cndmask_b32_e64 v131, v131, v148, s[42:43]
	s_waitcnt lgkmcnt(4)
	v_add_f32_e32 v152, v152, v153
	v_add_f32_e32 v130, v134, v130
	v_cndmask_b32_e64 v131, v131, v150, s[44:45]
	s_waitcnt lgkmcnt(3)
	v_add_f32_e32 v164, v164, v165
	v_fmamk_f32 v130, v130, 0x3a800000, v201
	v_cndmask_b32_e64 v131, v131, v152, s[46:47]
	s_waitcnt lgkmcnt(2)
	v_add_f32_e32 v172, v172, v173
	v_cndmask_b32_e64 v131, v131, v164, s[48:49]
	v_rsq_f32_e32 v130, v130
	s_waitcnt lgkmcnt(1)
	v_add_f32_e32 v174, v174, v175
	v_cndmask_b32_e64 v131, v131, v172, s[50:51]
	s_waitcnt lgkmcnt(0)
	v_add_f32_e32 v176, v176, v177
	v_cndmask_b32_e64 v131, v131, v174, s[52:53]
	v_cndmask_b32_e64 v131, v131, v176, s[54:55]
	v_mul_f32_e32 v131, v130, v131
	s_and_saveexec_b64 s[0:1], s[38:39]
	s_xor_b64 s[14:15], exec, s[0:1]
	s_cbranch_execz .LBB0_625
	v_mov_b32_e32 v130, v203
	s_waitcnt vmcnt(0)
	v_add_f32_e32 v130, v131, v130
	v_mul_f32_e32 v131, 0x3fb8aa3b, v130
	v_exp_f32_e32 v131, v131
	v_cmp_lt_f32_e64 s[0:1], s57, v130
	v_add_f32_e32 v131, 1.0, v131
	v_log_f32_e32 v131, v131
	s_nop 0
	v_mul_f32_e32 v131, 0x3f317218, v131
	v_cndmask_b32_e64 v130, v131, v130, s[0:1]
	v_mov_b32_e32 v131, v205
	s_waitcnt vmcnt(0)
	v_mul_f32_e32 v131, 0x3fb8aa3b, v131
	v_exp_f32_e32 v131, v131
	s_nop 0
	v_mul_f32_e64 v130, v130, -v131
